# hand-scheduled steady-state loop for prompt differential attention: LDS fragments fetched one half-step ahead, softmax VALU spread over MFMA gaps, SGPR-base tile loads
# speedup vs baseline: 1.0661x; 1.0535x over previous
.LBB0_777:
	s_cmp_lg_u32 0x100, -1
	s_cselect_b32 s8, 0x100, 0
	s_add_i32 s9, s8, 0x6800
	s_addk_i32 s8, 0x4000
	v_add_u32_e32 v230, s9, v153
	v_add_u32_e32 v233, s8, v153
	v_mov_b32_e32 v153, v0
	v_lshlrev_b32_e32 v231, 1, v155
	v_lshl_add_u64 v[200:201], s[6:7], 0, v[152:153]
	s_lshl_b32 s6, s37, 1
	s_lshl_b32 s3, s3, 2
	v_and_b32_e32 v229, 63, v154
	s_mov_b32 s24, 2
	v_add_u32_e32 v232, 2, v231
	s_mov_b32 s25, 0
	s_add_i32 s26, s36, 2
	v_or_b32_e32 v234, 1, v231
	s_sub_i32 s3, s6, s3
	s_mov_b32 s27, 0x12000
	s_mov_b32 s6, 0x9000
	s_movk_i32 s12, 0xc0
	s_movk_i32 s29, 0xff03
	v_readfirstlane_b32 s100, v231
	s_waitcnt vmcnt(1)
	ds_write_b128 v205, v[136:139] offset:53248
	s_waitcnt vmcnt(0)
	ds_write_b128 v205, v[140:143] offset:63488
	s_waitcnt lgkmcnt(0)
	s_barrier
.LBB0_778:
	s_cmp_lt_i32 s24, s100
	s_cbranch_scc0 .LfA_generic
	s_add_i32 s7, s29, 0xfe
	s_cmp_lt_u32 s7, s36
	s_cbranch_scc1 .LfA_enter

.LfA_enter:
	s_mov_b32 s30, s6
	v_and_b32_e32 v246, 15, v184
	v_lshlrev_b32_e32 v246, 4, v246
	v_lshl_add_u32 v246, v196, 1, v246
	s_lshl_b64 s[8:9], s[12:13], 13
	s_add_u32 s98, s10, s28
	s_addc_u32 s99, s11, 0
	s_add_u32 s98, s98, s8
	s_addc_u32 s99, s99, s9
	s_mov_b32 s101, 0
	v_add_u32_e32 v1, s27, v227
	v_add_u32_e32 v14, v1, v207
	v_add_u32_e32 v15, v1, v224
	v_add_u32_e32 v235, v1, v225
	v_add_u32_e32 v244, v1, v226
	v_add_u32_e32 v1, s30, v227
	v_add_u32_e32 v245, v1, v207
	ds_read_b128 v[2:5], v245 offset:8192
	v_add_u32_e32 v245, v1, v224
	ds_read_b128 v[6:9], v245 offset:8192
	v_add_u32_e32 v245, v1, v225
	ds_read_b128 v[10:13], v245 offset:8192
	v_add_u32_e32 v245, v1, v226
	ds_read_b128 v[152:155], v245 offset:8192
	v_add_u32_e32 v245, s25, v233
	ds_read_b64_tr_b16 v[156:157], v245 offset:10240
	ds_read_b64_tr_b16 v[158:159], v245 offset:12800
	ds_read_b64_tr_b16 v[160:161], v245 offset:10304
	ds_read_b64_tr_b16 v[162:163], v245 offset:12864
	ds_read_b64_tr_b16 v[164:165], v245 offset:10368
	ds_read_b64_tr_b16 v[166:167], v245 offset:12928
	ds_read_b64_tr_b16 v[168:169], v245 offset:10432
	ds_read_b64_tr_b16 v[170:171], v245 offset:12992
	s_waitcnt lgkmcnt(0)
	s_setprio 1
.LfA_iter:
	global_load_dwordx4 v[128:131], v246, s[98:99] offset:1024
	s_add_u32 s8, s98, 0x40000
	s_addc_u32 s9, s99, 0
	global_load_dwordx4 v[132:135], v246, s[8:9] offset:1024
	s_sub_u32 s18, s98, 0x80000
	s_subb_u32 s19, s99, 0
	global_load_dwordx4 v[136:139], v246, s[18:19] offset:2048
	s_sub_u32 s20, s98, 0x40000
	s_subb_u32 s21, s99, 0
	global_load_dwordx4 v[140:143], v246, s[20:21] offset:2048
	s_add_u32 s98, s98, 0x80000
	s_addc_u32 s99, s99, 0
	v_add_u32_e32 v1, s30, v233
	s_waitcnt lgkmcnt(3)
	v_mfma_f32_32x32x16_bf16 v[80:95], v[2:5], v[112:115], 0
	ds_read_b64_tr_b16 v[2:3], v245 offset:15360
	ds_read_b64_tr_b16 v[4:5], v245 offset:17920
	v_exp_f32_e32 v96, v96
	v_exp_f32_e32 v97, v97
	v_add_u32_e32 v14, s101, v14
	v_add_u32_e32 v15, s101, v15
	v_mfma_f32_32x32x16_bf16 v[64:79], v[156:159], v[148:151], v[64:79]
	ds_read_b64_tr_b16 v[156:157], v1 offset:0
	ds_read_b64_tr_b16 v[158:159], v1 offset:2560
	v_exp_f32_e32 v98, v98
	v_exp_f32_e32 v99, v99
	v_add_f32_e32 v228, v228, v96
	v_add_u32_e32 v235, s101, v235
	s_waitcnt lgkmcnt(6)
	v_mfma_f32_32x32x16_bf16 v[80:95], v[6:9], v[116:119], v[80:95]
	ds_read_b64_tr_b16 v[6:7], v245 offset:15424
	ds_read_b64_tr_b16 v[8:9], v245 offset:17984
	v_exp_f32_e32 v100, v100
	v_exp_f32_e32 v101, v101
	v_add_f32_e32 v228, v228, v97
	v_add_u32_e32 v244, s101, v244
	v_mfma_f32_32x32x16_bf16 v[48:63], v[160:163], v[148:151], v[48:63]
	ds_read_b64_tr_b16 v[160:161], v1 offset:64
	ds_read_b64_tr_b16 v[162:163], v1 offset:2624
	v_exp_f32_e32 v102, v102
	v_exp_f32_e32 v103, v103
	v_add_f32_e32 v228, v228, v98
	v_add_f32_e32 v228, v228, v99
	s_waitcnt lgkmcnt(9)
	v_mfma_f32_32x32x16_bf16 v[80:95], v[10:13], v[120:123], v[80:95]
	ds_read_b64_tr_b16 v[10:11], v245 offset:15488
	ds_read_b64_tr_b16 v[12:13], v245 offset:18048
	v_exp_f32_e32 v104, v104
	v_exp_f32_e32 v105, v105
	v_add_f32_e32 v228, v228, v100
	v_add_f32_e32 v228, v228, v101
	v_mfma_f32_32x32x16_bf16 v[16:31], v[164:167], v[148:151], v[16:31]
	ds_read_b64_tr_b16 v[164:165], v1 offset:128
	ds_read_b64_tr_b16 v[166:167], v1 offset:2688
	v_exp_f32_e32 v106, v106
	v_exp_f32_e32 v107, v107
	v_add_f32_e32 v228, v228, v102
	v_add_f32_e32 v228, v228, v103
	s_waitcnt lgkmcnt(12)
	v_mfma_f32_32x32x16_bf16 v[80:95], v[152:155], v[124:127], v[80:95]
	ds_read_b64_tr_b16 v[152:153], v245 offset:15552
	ds_read_b64_tr_b16 v[154:155], v245 offset:18112
	v_exp_f32_e32 v108, v108
	v_exp_f32_e32 v109, v109
	v_add_f32_e32 v228, v228, v104
	v_add_f32_e32 v228, v228, v105
	v_mfma_f32_32x32x16_bf16 v[32:47], v[168:171], v[148:151], v[32:47]
	ds_read_b64_tr_b16 v[168:169], v1 offset:192
	ds_read_b64_tr_b16 v[170:171], v1 offset:2752
	v_exp_f32_e32 v110, v110
	v_exp_f32_e32 v111, v111
	v_add_f32_e32 v228, v228, v106
	v_add_f32_e32 v228, v228, v107
	s_waitcnt lgkmcnt(14)
	v_mfma_f32_32x32x16_bf16 v[64:79], v[2:5], v[144:147], v[64:79]
	ds_read_b128 v[236:239], v14
	v_cvt_pk_bf16_f32 v148, v96, v97
	v_cvt_pk_bf16_f32 v149, v98, v99
	v_cvt_pk_bf16_f32 v150, v100, v101
	v_cvt_pk_bf16_f32 v151, v102, v103
	v_add_f32_e32 v228, v228, v108
	s_waitcnt lgkmcnt(11)
	v_mfma_f32_32x32x16_bf16 v[48:63], v[6:9], v[144:147], v[48:63]
	ds_read_b128 v[240:243], v15
	v_add_f32_e32 v228, v228, v109
	v_add_f32_e32 v228, v228, v110
	v_add_f32_e32 v228, v228, v111
	s_waitcnt lgkmcnt(8)
	v_mfma_f32_32x32x16_bf16 v[16:31], v[10:13], v[144:147], v[16:31]
	ds_read_b128 v[248:251], v235
	v_mov_b32_e32 v245, v1
	s_waitcnt lgkmcnt(5)
	v_mfma_f32_32x32x16_bf16 v[32:47], v[152:155], v[144:147], v[32:47]
	ds_read_b128 v[252:255], v244
	v_cvt_pk_bf16_f32 v144, v104, v105
	v_cvt_pk_bf16_f32 v145, v106, v107
	v_cvt_pk_bf16_f32 v146, v108, v109
	v_cvt_pk_bf16_f32 v147, v110, v111
	s_waitcnt lgkmcnt(3)
	v_mfma_f32_32x32x16_bf16 v[96:111], v[236:239], v[112:115], 0
	ds_read_b64_tr_b16 v[236:237], v245 offset:5120
	ds_read_b64_tr_b16 v[238:239], v245 offset:7680
	v_exp_f32_e32 v80, v80
	v_exp_f32_e32 v81, v81
	v_mfma_f32_32x32x16_bf16 v[64:79], v[156:159], v[148:151], v[64:79]
	ds_read_b64_tr_b16 v[156:157], v245 offset:10240
	ds_read_b64_tr_b16 v[158:159], v245 offset:12800
	v_exp_f32_e32 v82, v82
	v_exp_f32_e32 v83, v83
	v_add_f32_e32 v228, v228, v80
	s_waitcnt lgkmcnt(6)
	v_mfma_f32_32x32x16_bf16 v[96:111], v[240:243], v[116:119], v[96:111]
	ds_read_b64_tr_b16 v[240:241], v245 offset:5184
	ds_read_b64_tr_b16 v[242:243], v245 offset:7744
	v_exp_f32_e32 v84, v84
	v_exp_f32_e32 v85, v85
	v_add_f32_e32 v228, v228, v81
	v_mfma_f32_32x32x16_bf16 v[48:63], v[160:163], v[148:151], v[48:63]
	ds_read_b64_tr_b16 v[160:161], v245 offset:10304
	ds_read_b64_tr_b16 v[162:163], v245 offset:12864
	v_exp_f32_e32 v86, v86
	v_exp_f32_e32 v87, v87
	v_add_f32_e32 v228, v228, v82
	v_add_f32_e32 v228, v228, v83
	s_waitcnt lgkmcnt(9)
	v_mfma_f32_32x32x16_bf16 v[96:111], v[248:251], v[120:123], v[96:111]
	ds_read_b64_tr_b16 v[248:249], v245 offset:5248
	ds_read_b64_tr_b16 v[250:251], v245 offset:7808
	v_exp_f32_e32 v88, v88
	v_exp_f32_e32 v89, v89
	v_add_f32_e32 v228, v228, v84
	v_add_f32_e32 v228, v228, v85
	v_mfma_f32_32x32x16_bf16 v[16:31], v[164:167], v[148:151], v[16:31]
	ds_read_b64_tr_b16 v[164:165], v245 offset:10368
	ds_read_b64_tr_b16 v[166:167], v245 offset:12928
	v_exp_f32_e32 v90, v90
	v_exp_f32_e32 v91, v91
	v_add_f32_e32 v228, v228, v86
	v_add_f32_e32 v228, v228, v87
	s_waitcnt lgkmcnt(12)
	v_mfma_f32_32x32x16_bf16 v[96:111], v[252:255], v[124:127], v[96:111]
	ds_read_b64_tr_b16 v[252:253], v245 offset:5312
	ds_read_b64_tr_b16 v[254:255], v245 offset:7872
	v_exp_f32_e32 v92, v92
	v_exp_f32_e32 v93, v93
	v_add_f32_e32 v228, v228, v88
	v_add_f32_e32 v228, v228, v89
	v_mfma_f32_32x32x16_bf16 v[32:47], v[168:171], v[148:151], v[32:47]
	ds_read_b64_tr_b16 v[168:169], v245 offset:10432
	ds_read_b64_tr_b16 v[170:171], v245 offset:12992
	v_exp_f32_e32 v94, v94
	v_exp_f32_e32 v95, v95
	v_add_f32_e32 v228, v228, v90
	v_add_f32_e32 v228, v228, v91
	s_waitcnt lgkmcnt(14)
	v_mfma_f32_32x32x16_bf16 v[64:79], v[236:239], v[144:147], v[64:79]
	s_waitcnt vmcnt(0)
	v_add_u32_e32 v1, s25, v206
	ds_write_b128 v1, v[128:131]
	ds_write_b128 v1, v[132:135] offset:8192
	v_cvt_pk_bf16_f32 v148, v80, v81
	v_cvt_pk_bf16_f32 v149, v82, v83
	v_cvt_pk_bf16_f32 v150, v84, v85
	v_cvt_pk_bf16_f32 v151, v86, v87
	v_add_f32_e32 v228, v228, v92
	s_waitcnt lgkmcnt(12)
	v_mfma_f32_32x32x16_bf16 v[48:63], v[240:243], v[144:147], v[48:63]
	v_add_u32_e32 v1, s27, v205
	ds_write_b128 v1, v[136:139] offset:16384
	ds_write_b128 v1, v[140:143] offset:26624
	v_add_f32_e32 v228, v228, v93
	v_add_f32_e32 v228, v228, v94
	v_add_f32_e32 v228, v228, v95
	s_waitcnt lgkmcnt(10)
	v_mfma_f32_32x32x16_bf16 v[16:31], v[248:251], v[144:147], v[16:31]
	ds_read_b128 v[2:5], v14 offset:8192
	ds_read_b128 v[6:9], v15 offset:8192
	s_waitcnt lgkmcnt(8)
	v_mfma_f32_32x32x16_bf16 v[32:47], v[252:255], v[144:147], v[32:47]
	ds_read_b128 v[10:13], v235 offset:8192
	ds_read_b128 v[152:155], v244 offset:8192
	v_cvt_pk_bf16_f32 v144, v88, v89
	v_cvt_pk_bf16_f32 v145, v90, v91
	v_cvt_pk_bf16_f32 v146, v92, v93
	v_cvt_pk_bf16_f32 v147, v94, v95
	s_sub_i32 s101, s25, s27
	s_mov_b32 s6, s30
	s_mov_b32 s30, s27
	s_mov_b32 s27, s25
	s_mov_b32 s25, s6
	s_add_i32 s12, s12, 64
	s_add_i32 s24, s24, 2
	s_add_i32 s29, s29, 1
	s_waitcnt lgkmcnt(4)
	s_barrier
	s_cmp_lt_i32 s24, s100
	s_cbranch_scc0 .LfA_exit
	s_add_i32 s7, s29, 0xfe
	s_cmp_lt_u32 s7, s36
	s_cbranch_scc1 .LfA_iter
.LfA_exit:
	s_waitcnt lgkmcnt(0)
	s_setprio 0
	s_mov_b32 s6, s30
	s_branch .LfA_generic

	.amdhsa_kernel _Z11mega_kernel6Params
		.amdhsa_group_segment_fixed_size 49408
		.amdhsa_private_segment_fixed_size 0
		.amdhsa_kernarg_size 464
		.amdhsa_user_sgpr_count 2
		.amdhsa_user_sgpr_dispatch_ptr 0
		.amdhsa_user_sgpr_queue_ptr 0
		.amdhsa_user_sgpr_kernarg_segment_ptr 1
		.amdhsa_user_sgpr_dispatch_id 0
		.amdhsa_user_sgpr_kernarg_preload_length 0
		.amdhsa_user_sgpr_kernarg_preload_offset 0
		.amdhsa_user_sgpr_private_segment_size 0
		.amdhsa_uses_dynamic_stack 0
		.amdhsa_enable_private_segment 0
		.amdhsa_system_sgpr_workgroup_id_x 1
		.amdhsa_system_sgpr_workgroup_id_y 1
		.amdhsa_system_sgpr_workgroup_id_z 1
		.amdhsa_system_sgpr_workgroup_info 0
		.amdhsa_system_vgpr_workitem_id 2
		.amdhsa_next_free_vgpr 256
		.amdhsa_next_free_sgpr 102
		.amdhsa_accum_offset 256
		.amdhsa_reserve_vcc 1
		.amdhsa_float_round_mode_32 0
		.amdhsa_float_round_mode_16_64 0
		.amdhsa_float_denorm_mode_32 3
		.amdhsa_float_denorm_mode_16_64 3
		.amdhsa_dx10_clamp 1
		.amdhsa_ieee_mode 1
		.amdhsa_fp16_overflow 0
		.amdhsa_tg_split 0
		.amdhsa_exception_fp_ieee_invalid_op 0
		.amdhsa_exception_fp_denorm_src 0
		.amdhsa_exception_fp_ieee_div_zero 0
		.amdhsa_exception_fp_ieee_overflow 0
		.amdhsa_exception_fp_ieee_underflow 0
		.amdhsa_exception_fp_ieee_inexact 0
		.amdhsa_exception_int_div_zero 0
	.end_amdhsa_kernel

amdhsa.kernels:
  - .agpr_count:     0
    .args:
      - .offset:         0
        .size:           208
        .value_kind:     by_value
      - .offset:         208
        .size:           4
        .value_kind:     hidden_block_count_x
      - .offset:         212
        .size:           4
        .value_kind:     hidden_block_count_y
      - .offset:         216
        .size:           4
        .value_kind:     hidden_block_count_z
      - .offset:         220
        .size:           2
        .value_kind:     hidden_group_size_x
      - .offset:         222
        .size:           2
        .value_kind:     hidden_group_size_y
      - .offset:         224
        .size:           2
        .value_kind:     hidden_group_size_z
      - .offset:         226
        .size:           2
        .value_kind:     hidden_remainder_x
      - .offset:         228
        .size:           2
        .value_kind:     hidden_remainder_y
      - .offset:         230
        .size:           2
        .value_kind:     hidden_remainder_z
      - .offset:         248
        .size:           8
        .value_kind:     hidden_global_offset_x
      - .offset:         256
        .size:           8
        .value_kind:     hidden_global_offset_y
      - .offset:         264
        .size:           8
        .value_kind:     hidden_global_offset_z
      - .offset:         272
        .size:           2
        .value_kind:     hidden_grid_dims
      - .offset:         328
        .size:           4
        .value_kind:     hidden_dynamic_lds_size
    .group_segment_fixed_size: 49408
    .kernarg_segment_align: 8
    .kernarg_segment_size: 464
    .language:       OpenCL C
    .language_version:
      - 2
      - 0
    .max_flat_workgroup_size: 512
    .name:           _Z11mega_kernel6Params
    .private_segment_fixed_size: 0
    .sgpr_count:     108
    .sgpr_spill_count: 85
    .symbol:         _Z11mega_kernel6Params.kd
    .uniform_work_group_size: 1
    .uses_dynamic_stack: false
    .vgpr_count:     256
    .vgpr_spill_count: 0
    .wavefront_size: 64
